# MLA kv up-projection GEMM: per-tile row sum-of-squares records prefetched to LDS by LDS-DMA (same scheme as in-proj / FFN-up)
# baseline (speedup 1.0000x reference)
; #define PG8_BAR __builtin_amdgcn_s_barrier()
; template <class Epi>
; __device__ __forceinline__ void gemm_phase(LAS unsigned char* lds, const Gemm g, const Epi& E) {
;     ...
;         for (int a = 0; a < 2; ++a)
; #pragma unroll
;             for (int b = 0; b < 2; ++b)
; #pragma unroll
;                 for (int m = 0; m < 4; ++m)
; #pragma unroll
;                     for (int n = 0; n < 2; ++n) acc[a][b][m][n] = (f32x4){0.f, 0.f, 0.f, 0.f};
;         cur = nxt; cA = nA; cB = nB; ++ui;
;         if (wr == 1) PG8_BAR;
.LBB0_383:
	s_andn2_b64 vcc, exec, s[38:39]
	s_cbranch_vccnz .LBB0_386
	s_and_b64 vcc, exec, s[44:45]
	s_cbranch_vccnz .Lukv_ssq_skip
	v_lshl_add_u32 v150, s58, 8, v208
	v_mov_b32_e32 v151, 0
	v_subrev_u32_e32 v150, 0x100, v150
	v_readfirstlane_b32 s20, v208
	v_lshl_add_u64 v[150:151], v[150:151], 4, s[88:89]
	s_nop 1
	s_lshl_b32 s20, s20, 4
	s_add_i32 s20, s20, 0x20400
	s_mov_b32 m0, s20
	s_nop 0
	global_load_lds_dwordx4 v[150:151], off
.Lukv_ssq_skip:
	s_add_u32 s48, s48, 0x80
	s_addc_u32 s49, s49, 0
	s_add_u32 s20, s50, 0x100
	s_addc_u32 s21, s51, 0
	s_mov_b32 s50, 0
	v_mov_b64_e32 v[2:3], 0
	v_mov_b64_e32 v[4:5], 0
	v_mov_b64_e32 v[6:7], 0
	v_mov_b64_e32 v[8:9], 0
	v_mov_b64_e32 v[10:11], 0
	v_mov_b64_e32 v[12:13], 0
	v_mov_b64_e32 v[14:15], 0
	v_mov_b64_e32 v[16:17], 0
	v_mov_b64_e32 v[18:19], 0
	v_mov_b64_e32 v[20:21], 0
	v_mov_b64_e32 v[22:23], 0
	v_mov_b64_e32 v[24:25], 0
	v_mov_b64_e32 v[26:27], 0
	v_mov_b64_e32 v[28:29], 0
	v_mov_b64_e32 v[30:31], 0
	v_mov_b64_e32 v[32:33], 0
	v_mov_b64_e32 v[34:35], 0
	v_mov_b64_e32 v[36:37], 0
	v_mov_b64_e32 v[38:39], 0
	v_mov_b64_e32 v[40:41], 0
	v_mov_b64_e32 v[42:43], 0
	v_mov_b64_e32 v[44:45], 0
	v_mov_b64_e32 v[46:47], 0
	v_mov_b64_e32 v[48:49], 0
	v_mov_b64_e32 v[50:51], 0
	v_mov_b64_e32 v[52:53], 0
	v_mov_b64_e32 v[54:55], 0
	v_mov_b64_e32 v[56:57], 0
	v_mov_b64_e32 v[58:59], 0
	v_mov_b64_e32 v[60:61], 0
	v_mov_b64_e32 v[62:63], 0
	v_mov_b64_e32 v[64:65], 0
	v_mov_b64_e32 v[66:67], 0
	v_mov_b64_e32 v[68:69], 0
	v_mov_b64_e32 v[70:71], 0
	v_mov_b64_e32 v[72:73], 0
	v_mov_b64_e32 v[74:75], 0
	v_mov_b64_e32 v[76:77], 0
	v_mov_b64_e32 v[78:79], 0
	v_mov_b64_e32 v[80:81], 0
	v_mov_b64_e32 v[82:83], 0
	v_mov_b64_e32 v[84:85], 0
	v_mov_b64_e32 v[86:87], 0
	v_mov_b64_e32 v[88:89], 0
	v_mov_b64_e32 v[90:91], 0
	v_mov_b64_e32 v[92:93], 0
	v_mov_b64_e32 v[94:95], 0
	v_mov_b64_e32 v[96:97], 0
	v_mov_b64_e32 v[98:99], 0
	v_mov_b64_e32 v[100:101], 0
	v_mov_b64_e32 v[102:103], 0
	v_mov_b64_e32 v[104:105], 0
	v_mov_b64_e32 v[106:107], 0
	v_mov_b64_e32 v[108:109], 0
	v_mov_b64_e32 v[110:111], 0
	v_mov_b64_e32 v[112:113], 0
	v_mov_b64_e32 v[114:115], 0
	v_mov_b64_e32 v[116:117], 0
	v_mov_b64_e32 v[118:119], 0
	v_mov_b64_e32 v[120:121], 0
	v_mov_b64_e32 v[122:123], 0
	v_mov_b64_e32 v[124:125], 0
	v_mov_b64_e32 v[126:127], 0
	v_mov_b64_e32 v[128:129], 0

; __device__ __forceinline__ unsigned cvtpk(float lo, float hi) { f32x2 v = {lo, hi}; bf16x2_t b = __builtin_convertvector(v, bf16x2_t); return __builtin_bit_cast(unsigned, b); }
;     __device__ __forceinline__ void operator()(AccRef acc, const Unit& u, int wr, int wc, int fr, int fq) const {
;     ...
;             for (int m = 0; m < 4; ++m) {
;                 const int row = row0 + ai * 128 + m * 16;
;                 const float rs = rsqrtf(ssq_sum<NS>(ssq + (size_t)row * NS) * inv_n + EPS);
;                 bf16_t* rowp = O + (size_t)row * ldc + col0;
; #pragma unroll
;                 for (int bj = 0; bj < 2; ++bj) {
;                     f32x4 v0 = acc[ai][bj][m][0] * rs, v1 = acc[ai][bj][m][1] * rs;
;                     if (ROPE) { const int g32 = u.pn * 8 + bj * 4 + wc; if (g32 % 3 == 2) { const int pos = row & (SEQ - 1); rope8(v0, v1, cost + pos * 16, sint + pos * 16, fq); } }
;                     u32x4 w; w.x = cvtpk(v0[0], v0[1]); w.y = cvtpk(v0[2], v0[3]); w.z = cvtpk(v1[0], v1[1]); w.w = cvtpk(v1[2], v1[3]);
;                     st16_wt(rowp + bj * 128, w);
;                 }
.LBB0_388:
	v_lshl_add_u32 v144, s58, 8, v146
	v_ashrrev_i32_e32 v145, 31, v144
	v_and_b32_e32 v140, 0xff, v144
	v_lshlrev_b32_e32 v140, 4, v140
	v_add_u32_e32 v140, 0x21400, v140
	ds_read_b128 v[140:143], v140
	v_lshl_or_b32 v150, s55, 8, v148
	v_ashrrev_i32_e32 v151, 31, v150
	s_waitcnt lgkmcnt(0)
	v_mov_b32_e32 v152, v141
	v_mov_b32_e32 v153, v142
	v_mov_b32_e32 v141, v143
	v_pk_add_f32 v[140:141], v[152:153], v[140:141]
	v_lshlrev_b64 v[142:143], 1, v[150:151]
	v_add_f32_e32 v140, v140, v141
	v_add_f32_e32 v140, 0, v140
	v_fmamk_f32 v140, v140, 0x3c000000, v212
	v_cmp_gt_f32_e32 vcc, s69, v140
	v_mul_f32_e32 v141, 0x4b800000, v140
	s_nop 0
	v_cndmask_b32_e32 v140, v140, v141, vcc
	v_rsq_f32_e32 v140, v140
	s_nop 0
	v_mul_f32_e32 v141, 0x45800000, v140
	v_cndmask_b32_e32 v152, v140, v141, vcc
	v_mov_b64_e32 v[140:141], s[94:95]
	v_mad_i64_i32 v[154:155], s[20:21], v144, s33, v[140:141]
	v_pk_mul_f32 v[124:125], v[124:125], v[152:153] op_sel_hi:[1,0]
	v_pk_mul_f32 v[122:123], v[122:123], v[152:153] op_sel_hi:[1,0]
	v_pk_mul_f32 v[128:129], v[128:129], v[152:153] op_sel_hi:[1,0]
	v_pk_mul_f32 v[126:127], v[126:127], v[152:153] op_sel_hi:[1,0]
	v_lshl_add_u64 v[150:151], v[154:155], 0, v[142:143]
	v_cvt_pk_bf16_f32 v122, v122, v123
	v_cvt_pk_bf16_f32 v123, v124, v125
	v_cvt_pk_bf16_f32 v124, v126, v127
	v_cvt_pk_bf16_f32 v125, v128, v129
	global_store_dwordx4 v[150:151], v[122:125], off
	v_pk_mul_f32 v[120:121], v[120:121], v[152:153] op_sel_hi:[1,0]
	v_pk_mul_f32 v[118:119], v[118:119], v[152:153] op_sel_hi:[1,0]
	v_pk_mul_f32 v[122:123], v[116:117], v[152:153] op_sel_hi:[1,0]
	v_pk_mul_f32 v[116:117], v[114:115], v[152:153] op_sel_hi:[1,0]
	v_cvt_pk_bf16_f32 v114, v118, v119
	v_cvt_pk_bf16_f32 v115, v120, v121
	v_cvt_pk_bf16_f32 v116, v116, v117
	v_cvt_pk_bf16_f32 v117, v122, v123
	v_or_b32_e32 v118, 16, v144
	global_store_dwordx4 v[150:151], v[114:117], off offset:256
	v_ashrrev_i32_e32 v119, 31, v118
	s_nop 0
	v_and_b32_e32 v114, 0xff, v118
	v_lshlrev_b32_e32 v114, 4, v114
	v_add_u32_e32 v114, 0x21400, v114
	ds_read_b128 v[114:117], v114
	s_waitcnt lgkmcnt(0)
	v_mov_b32_e32 v120, v115
	v_mov_b32_e32 v121, v116
	v_mov_b32_e32 v115, v117
	v_pk_add_f32 v[114:115], v[120:121], v[114:115]
	v_mad_i64_i32 v[116:117], s[20:21], v118, s33, v[140:141]
	v_add_f32_e32 v114, v114, v115
	v_add_f32_e32 v114, 0, v114
	v_fmamk_f32 v114, v114, 0x3c000000, v212
	v_cmp_gt_f32_e32 vcc, s69, v114
	v_mul_f32_e32 v115, 0x4b800000, v114
	v_lshl_add_u64 v[116:117], v[116:117], 0, v[142:143]
	v_cndmask_b32_e32 v114, v114, v115, vcc
	v_rsq_f32_e32 v114, v114
	s_nop 0
	v_mul_f32_e32 v115, 0x45800000, v114
	v_cndmask_b32_e32 v114, v114, v115, vcc
	v_pk_mul_f32 v[112:113], v[112:113], v[114:115] op_sel_hi:[1,0]
	v_pk_mul_f32 v[110:111], v[110:111], v[114:115] op_sel_hi:[1,0]
	v_pk_mul_f32 v[118:119], v[108:109], v[114:115] op_sel_hi:[1,0]
	v_pk_mul_f32 v[108:109], v[106:107], v[114:115] op_sel_hi:[1,0]
	v_cvt_pk_bf16_f32 v106, v110, v111
	v_cvt_pk_bf16_f32 v107, v112, v113
	v_cvt_pk_bf16_f32 v108, v108, v109
	v_cvt_pk_bf16_f32 v109, v118, v119
	global_store_dwordx4 v[116:117], v[106:109], off
	v_pk_mul_f32 v[104:105], v[104:105], v[114:115] op_sel_hi:[1,0]
	v_pk_mul_f32 v[102:103], v[102:103], v[114:115] op_sel_hi:[1,0]
	v_pk_mul_f32 v[106:107], v[100:101], v[114:115] op_sel_hi:[1,0]
	v_pk_mul_f32 v[100:101], v[98:99], v[114:115] op_sel_hi:[1,0]
	v_cvt_pk_bf16_f32 v98, v102, v103
	v_cvt_pk_bf16_f32 v99, v104, v105
	v_cvt_pk_bf16_f32 v100, v100, v101
	v_cvt_pk_bf16_f32 v101, v106, v107
	v_or_b32_e32 v102, 32, v144
	global_store_dwordx4 v[116:117], v[98:101], off offset:256
	v_ashrrev_i32_e32 v103, 31, v102
	s_nop 0
	v_and_b32_e32 v98, 0xff, v102
	v_lshlrev_b32_e32 v98, 4, v98
	v_add_u32_e32 v98, 0x21400, v98
	ds_read_b128 v[98:101], v98
	s_waitcnt lgkmcnt(0)
	v_mov_b32_e32 v104, v99
	v_mov_b32_e32 v105, v100
	v_mov_b32_e32 v99, v101
	v_pk_add_f32 v[98:99], v[104:105], v[98:99]
	v_mad_i64_i32 v[100:101], s[20:21], v102, s33, v[140:141]
	v_add_f32_e32 v98, v98, v99
	v_add_f32_e32 v98, 0, v98
	v_fmamk_f32 v98, v98, 0x3c000000, v212
	v_cmp_gt_f32_e32 vcc, s69, v98
	v_mul_f32_e32 v99, 0x4b800000, v98
	v_lshl_add_u64 v[100:101], v[100:101], 0, v[142:143]
	v_cndmask_b32_e32 v98, v98, v99, vcc
	v_rsq_f32_e32 v98, v98
	s_nop 0
	v_mul_f32_e32 v99, 0x45800000, v98
	v_cndmask_b32_e32 v98, v98, v99, vcc
	v_pk_mul_f32 v[96:97], v[96:97], v[98:99] op_sel_hi:[1,0]
	v_pk_mul_f32 v[94:95], v[94:95], v[98:99] op_sel_hi:[1,0]
	v_pk_mul_f32 v[102:103], v[92:93], v[98:99] op_sel_hi:[1,0]
	v_pk_mul_f32 v[92:93], v[90:91], v[98:99] op_sel_hi:[1,0]
	v_cvt_pk_bf16_f32 v90, v94, v95
	v_cvt_pk_bf16_f32 v91, v96, v97
	v_cvt_pk_bf16_f32 v92, v92, v93
	v_cvt_pk_bf16_f32 v93, v102, v103
	global_store_dwordx4 v[100:101], v[90:93], off
	v_pk_mul_f32 v[88:89], v[88:89], v[98:99] op_sel_hi:[1,0]
	v_pk_mul_f32 v[86:87], v[86:87], v[98:99] op_sel_hi:[1,0]
	v_pk_mul_f32 v[90:91], v[84:85], v[98:99] op_sel_hi:[1,0]
	v_pk_mul_f32 v[84:85], v[82:83], v[98:99] op_sel_hi:[1,0]
	v_cvt_pk_bf16_f32 v82, v86, v87
	v_cvt_pk_bf16_f32 v83, v88, v89
	v_cvt_pk_bf16_f32 v84, v84, v85
	v_cvt_pk_bf16_f32 v85, v90, v91
	v_or_b32_e32 v86, 48, v144
	global_store_dwordx4 v[100:101], v[82:85], off offset:256
	v_ashrrev_i32_e32 v87, 31, v86
	s_nop 0
	v_and_b32_e32 v82, 0xff, v86
	v_lshlrev_b32_e32 v82, 4, v82
	v_add_u32_e32 v82, 0x21400, v82
	ds_read_b128 v[82:85], v82
	s_waitcnt lgkmcnt(0)
; __device__ __forceinline__ unsigned cvtpk(float lo, float hi) { f32x2 v = {lo, hi}; bf16x2_t b = __builtin_convertvector(v, bf16x2_t); return __builtin_bit_cast(unsigned, b); }
;     __device__ __forceinline__ void operator()(AccRef acc, const Unit& u, int wr, int wc, int fr, int fq) const {
;     ...
;             for (int m = 0; m < 4; ++m) {
;                 const int row = row0 + ai * 128 + m * 16;
;                 const float rs = rsqrtf(ssq_sum<NS>(ssq + (size_t)row * NS) * inv_n + EPS);
;                 bf16_t* rowp = O + (size_t)row * ldc + col0;
; #pragma unroll
;                 for (int bj = 0; bj < 2; ++bj) {
;                     f32x4 v0 = acc[ai][bj][m][0] * rs, v1 = acc[ai][bj][m][1] * rs;
;                     if (ROPE) { const int g32 = u.pn * 8 + bj * 4 + wc; if (g32 % 3 == 2) { const int pos = row & (SEQ - 1); rope8(v0, v1, cost + pos * 16, sint + pos * 16, fq); } }
;                     u32x4 w; w.x = cvtpk(v0[0], v0[1]); w.y = cvtpk(v0[2], v0[3]); w.z = cvtpk(v1[0], v1[1]); w.w = cvtpk(v1[2], v1[3]);
;                     st16_wt(rowp + bj * 128, w);
;                 }
	v_mov_b32_e32 v88, v83
	v_mov_b32_e32 v89, v84
	v_mov_b32_e32 v83, v85
	v_pk_add_f32 v[82:83], v[88:89], v[82:83]
	v_mad_i64_i32 v[84:85], s[20:21], v86, s33, v[140:141]
	v_add_f32_e32 v82, v82, v83
	v_add_f32_e32 v82, 0, v82
	v_fmamk_f32 v82, v82, 0x3c000000, v212
	v_cmp_gt_f32_e32 vcc, s69, v82
	v_mul_f32_e32 v83, 0x4b800000, v82
	v_lshl_add_u64 v[84:85], v[84:85], 0, v[142:143]
	v_cndmask_b32_e32 v82, v82, v83, vcc
	v_rsq_f32_e32 v82, v82
	s_nop 0
	v_mul_f32_e32 v83, 0x45800000, v82
	v_cndmask_b32_e32 v82, v82, v83, vcc
	v_pk_mul_f32 v[80:81], v[80:81], v[82:83] op_sel_hi:[1,0]
	v_pk_mul_f32 v[78:79], v[78:79], v[82:83] op_sel_hi:[1,0]
	v_pk_mul_f32 v[86:87], v[76:77], v[82:83] op_sel_hi:[1,0]
	v_pk_mul_f32 v[76:77], v[74:75], v[82:83] op_sel_hi:[1,0]
	v_cvt_pk_bf16_f32 v74, v78, v79
	v_cvt_pk_bf16_f32 v75, v80, v81
	v_cvt_pk_bf16_f32 v76, v76, v77
	v_cvt_pk_bf16_f32 v77, v86, v87
	global_store_dwordx4 v[84:85], v[74:77], off
	v_pk_mul_f32 v[72:73], v[72:73], v[82:83] op_sel_hi:[1,0]
	v_pk_mul_f32 v[70:71], v[70:71], v[82:83] op_sel_hi:[1,0]
	v_pk_mul_f32 v[74:75], v[68:69], v[82:83] op_sel_hi:[1,0]
	v_pk_mul_f32 v[68:69], v[66:67], v[82:83] op_sel_hi:[1,0]
	v_cvt_pk_bf16_f32 v66, v70, v71
	v_cvt_pk_bf16_f32 v67, v72, v73
	v_cvt_pk_bf16_f32 v68, v68, v69
	v_cvt_pk_bf16_f32 v69, v74, v75
	v_add_u32_e32 v70, 0x80, v144
	global_store_dwordx4 v[84:85], v[66:69], off offset:256
	v_ashrrev_i32_e32 v71, 31, v70
	s_nop 0
	v_and_b32_e32 v66, 0xff, v70
	v_lshlrev_b32_e32 v66, 4, v66
	v_add_u32_e32 v66, 0x21400, v66
	ds_read_b128 v[66:69], v66
	s_waitcnt lgkmcnt(0)
	v_mov_b32_e32 v72, v67
	v_mov_b32_e32 v73, v68
	v_mov_b32_e32 v67, v69
	v_pk_add_f32 v[66:67], v[72:73], v[66:67]
	v_mad_i64_i32 v[68:69], s[20:21], v70, s33, v[140:141]
	v_add_f32_e32 v66, v66, v67
	v_add_f32_e32 v66, 0, v66
	v_fmamk_f32 v66, v66, 0x3c000000, v212
	v_cmp_gt_f32_e32 vcc, s69, v66
	v_mul_f32_e32 v67, 0x4b800000, v66
	v_lshl_add_u64 v[68:69], v[68:69], 0, v[142:143]
	v_cndmask_b32_e32 v66, v66, v67, vcc
	v_rsq_f32_e32 v66, v66
	s_nop 0
	v_mul_f32_e32 v67, 0x45800000, v66
	v_cndmask_b32_e32 v66, v66, v67, vcc
	v_pk_mul_f32 v[64:65], v[64:65], v[66:67] op_sel_hi:[1,0]
	v_pk_mul_f32 v[62:63], v[62:63], v[66:67] op_sel_hi:[1,0]
	v_pk_mul_f32 v[70:71], v[60:61], v[66:67] op_sel_hi:[1,0]
	v_pk_mul_f32 v[60:61], v[58:59], v[66:67] op_sel_hi:[1,0]
	v_cvt_pk_bf16_f32 v58, v62, v63
	v_cvt_pk_bf16_f32 v59, v64, v65
	v_cvt_pk_bf16_f32 v60, v60, v61
	v_cvt_pk_bf16_f32 v61, v70, v71
	global_store_dwordx4 v[68:69], v[58:61], off
	v_pk_mul_f32 v[56:57], v[56:57], v[66:67] op_sel_hi:[1,0]
	v_pk_mul_f32 v[54:55], v[54:55], v[66:67] op_sel_hi:[1,0]
	v_pk_mul_f32 v[58:59], v[52:53], v[66:67] op_sel_hi:[1,0]
	v_pk_mul_f32 v[52:53], v[50:51], v[66:67] op_sel_hi:[1,0]
	v_cvt_pk_bf16_f32 v50, v54, v55
	v_cvt_pk_bf16_f32 v51, v56, v57
	v_cvt_pk_bf16_f32 v52, v52, v53
	v_cvt_pk_bf16_f32 v53, v58, v59
	v_add_u32_e32 v54, 0x90, v144
	global_store_dwordx4 v[68:69], v[50:53], off offset:256
	v_ashrrev_i32_e32 v55, 31, v54
	s_nop 0
	v_and_b32_e32 v50, 0xff, v54
	v_lshlrev_b32_e32 v50, 4, v50
	v_add_u32_e32 v50, 0x21400, v50
	ds_read_b128 v[50:53], v50
	s_waitcnt lgkmcnt(0)
; __device__ __forceinline__ unsigned cvtpk(float lo, float hi) { f32x2 v = {lo, hi}; bf16x2_t b = __builtin_convertvector(v, bf16x2_t); return __builtin_bit_cast(unsigned, b); }
;     __device__ __forceinline__ void operator()(AccRef acc, const Unit& u, int wr, int wc, int fr, int fq) const {
;     ...
;             for (int m = 0; m < 4; ++m) {
;                 const int row = row0 + ai * 128 + m * 16;
;                 const float rs = rsqrtf(ssq_sum<NS>(ssq + (size_t)row * NS) * inv_n + EPS);
;                 bf16_t* rowp = O + (size_t)row * ldc + col0;
; #pragma unroll
;                 for (int bj = 0; bj < 2; ++bj) {
;                     f32x4 v0 = acc[ai][bj][m][0] * rs, v1 = acc[ai][bj][m][1] * rs;
;                     if (ROPE) { const int g32 = u.pn * 8 + bj * 4 + wc; if (g32 % 3 == 2) { const int pos = row & (SEQ - 1); rope8(v0, v1, cost + pos * 16, sint + pos * 16, fq); } }
;                     u32x4 w; w.x = cvtpk(v0[0], v0[1]); w.y = cvtpk(v0[2], v0[3]); w.z = cvtpk(v1[0], v1[1]); w.w = cvtpk(v1[2], v1[3]);
;                     st16_wt(rowp + bj * 128, w);
;                 }
	v_mov_b32_e32 v56, v51
	v_mov_b32_e32 v57, v52
	v_mov_b32_e32 v51, v53
	v_pk_add_f32 v[50:51], v[56:57], v[50:51]
	v_mad_i64_i32 v[52:53], s[20:21], v54, s33, v[140:141]
	v_add_f32_e32 v50, v50, v51
	v_add_f32_e32 v50, 0, v50
	v_fmamk_f32 v50, v50, 0x3c000000, v212
	v_cmp_gt_f32_e32 vcc, s69, v50
	v_mul_f32_e32 v51, 0x4b800000, v50
	v_lshl_add_u64 v[52:53], v[52:53], 0, v[142:143]
	v_cndmask_b32_e32 v50, v50, v51, vcc
	v_rsq_f32_e32 v50, v50
	s_nop 0
	v_mul_f32_e32 v51, 0x45800000, v50
	v_cndmask_b32_e32 v50, v50, v51, vcc
	v_pk_mul_f32 v[48:49], v[48:49], v[50:51] op_sel_hi:[1,0]
	v_pk_mul_f32 v[46:47], v[46:47], v[50:51] op_sel_hi:[1,0]
	v_pk_mul_f32 v[54:55], v[44:45], v[50:51] op_sel_hi:[1,0]
	v_pk_mul_f32 v[44:45], v[42:43], v[50:51] op_sel_hi:[1,0]
	v_cvt_pk_bf16_f32 v42, v46, v47
	v_cvt_pk_bf16_f32 v43, v48, v49
	v_cvt_pk_bf16_f32 v44, v44, v45
	v_cvt_pk_bf16_f32 v45, v54, v55
	global_store_dwordx4 v[52:53], v[42:45], off
	v_pk_mul_f32 v[40:41], v[40:41], v[50:51] op_sel_hi:[1,0]
	v_pk_mul_f32 v[38:39], v[38:39], v[50:51] op_sel_hi:[1,0]
	v_pk_mul_f32 v[42:43], v[36:37], v[50:51] op_sel_hi:[1,0]
	v_pk_mul_f32 v[36:37], v[34:35], v[50:51] op_sel_hi:[1,0]
	v_cvt_pk_bf16_f32 v34, v38, v39
	v_cvt_pk_bf16_f32 v35, v40, v41
	v_cvt_pk_bf16_f32 v36, v36, v37
	v_cvt_pk_bf16_f32 v37, v42, v43
	v_add_u32_e32 v38, 0xa0, v144
	global_store_dwordx4 v[52:53], v[34:37], off offset:256
	v_ashrrev_i32_e32 v39, 31, v38
	s_nop 0
	v_and_b32_e32 v34, 0xff, v38
	v_lshlrev_b32_e32 v34, 4, v34
	v_add_u32_e32 v34, 0x21400, v34
	ds_read_b128 v[34:37], v34
	s_waitcnt lgkmcnt(0)
	v_mov_b32_e32 v40, v35
	v_mov_b32_e32 v41, v36
	v_mov_b32_e32 v35, v37
	v_pk_add_f32 v[34:35], v[40:41], v[34:35]
	v_mad_i64_i32 v[36:37], s[20:21], v38, s33, v[140:141]
	v_add_f32_e32 v34, v34, v35
	v_add_f32_e32 v34, 0, v34
	v_fmamk_f32 v34, v34, 0x3c000000, v212
	v_cmp_gt_f32_e32 vcc, s69, v34
	v_mul_f32_e32 v35, 0x4b800000, v34
	v_lshl_add_u64 v[36:37], v[36:37], 0, v[142:143]
	v_cndmask_b32_e32 v34, v34, v35, vcc
	v_rsq_f32_e32 v34, v34
	s_nop 0
	v_mul_f32_e32 v35, 0x45800000, v34
	v_cndmask_b32_e32 v34, v34, v35, vcc
	v_pk_mul_f32 v[32:33], v[32:33], v[34:35] op_sel_hi:[1,0]
	v_pk_mul_f32 v[30:31], v[30:31], v[34:35] op_sel_hi:[1,0]
	v_pk_mul_f32 v[38:39], v[28:29], v[34:35] op_sel_hi:[1,0]
	v_pk_mul_f32 v[28:29], v[26:27], v[34:35] op_sel_hi:[1,0]
	v_cvt_pk_bf16_f32 v26, v30, v31
	v_cvt_pk_bf16_f32 v27, v32, v33
	v_cvt_pk_bf16_f32 v28, v28, v29
	v_cvt_pk_bf16_f32 v29, v38, v39
	global_store_dwordx4 v[36:37], v[26:29], off
	v_pk_mul_f32 v[24:25], v[24:25], v[34:35] op_sel_hi:[1,0]
	v_pk_mul_f32 v[22:23], v[22:23], v[34:35] op_sel_hi:[1,0]
	v_pk_mul_f32 v[26:27], v[20:21], v[34:35] op_sel_hi:[1,0]
	v_pk_mul_f32 v[20:21], v[18:19], v[34:35] op_sel_hi:[1,0]
	v_cvt_pk_bf16_f32 v18, v22, v23
	v_cvt_pk_bf16_f32 v19, v24, v25
	v_cvt_pk_bf16_f32 v20, v20, v21
	v_cvt_pk_bf16_f32 v21, v26, v27
	v_add_u32_e32 v22, 0xb0, v144
	global_store_dwordx4 v[36:37], v[18:21], off offset:256
	v_ashrrev_i32_e32 v23, 31, v22
	s_nop 0
	v_and_b32_e32 v18, 0xff, v22
	v_lshlrev_b32_e32 v18, 4, v18
	v_add_u32_e32 v18, 0x21400, v18
	ds_read_b128 v[18:21], v18
	s_waitcnt lgkmcnt(0)
	v_mov_b32_e32 v24, v19
	v_mov_b32_e32 v25, v20
	v_mov_b32_e32 v19, v21
	v_pk_add_f32 v[18:19], v[24:25], v[18:19]
	v_mad_i64_i32 v[20:21], s[20:21], v22, s33, v[140:141]
	v_add_f32_e32 v18, v18, v19
	v_add_f32_e32 v18, 0, v18
	v_fmamk_f32 v18, v18, 0x3c000000, v212
	v_cmp_gt_f32_e32 vcc, s69, v18
	v_mul_f32_e32 v19, 0x4b800000, v18
	v_lshl_add_u64 v[20:21], v[20:21], 0, v[142:143]
	v_cndmask_b32_e32 v18, v18, v19, vcc
	v_rsq_f32_e32 v18, v18
	s_mov_b64 s[20:21], -1
	v_mul_f32_e32 v19, 0x45800000, v18
	v_cndmask_b32_e32 v18, v18, v19, vcc
	v_pk_mul_f32 v[16:17], v[16:17], v[18:19] op_sel_hi:[1,0]
	v_pk_mul_f32 v[14:15], v[14:15], v[18:19] op_sel_hi:[1,0]
	v_pk_mul_f32 v[22:23], v[12:13], v[18:19] op_sel_hi:[1,0]
	v_pk_mul_f32 v[12:13], v[10:11], v[18:19] op_sel_hi:[1,0]
	v_cvt_pk_bf16_f32 v10, v14, v15
	v_cvt_pk_bf16_f32 v11, v16, v17
	v_cvt_pk_bf16_f32 v12, v12, v13
	v_cvt_pk_bf16_f32 v13, v22, v23
	global_store_dwordx4 v[20:21], v[10:13], off
	v_pk_mul_f32 v[8:9], v[8:9], v[18:19] op_sel_hi:[1,0]
	v_pk_mul_f32 v[6:7], v[6:7], v[18:19] op_sel_hi:[1,0]
	v_pk_mul_f32 v[10:11], v[4:5], v[18:19] op_sel_hi:[1,0]
	v_pk_mul_f32 v[4:5], v[2:3], v[18:19] op_sel_hi:[1,0]
	v_cvt_pk_bf16_f32 v2, v6, v7
	v_cvt_pk_bf16_f32 v3, v8, v9
	v_cvt_pk_bf16_f32 v4, v4, v5
	v_cvt_pk_bf16_f32 v5, v10, v11
	global_store_dwordx4 v[20:21], v[2:5], off offset:256
	s_and_b64 vcc, exec, s[40:41]
	s_cbranch_vccnz .LBB0_372
	s_andn2_b64 vcc, exec, s[22:23]
	s_cbranch_vccnz .LBB0_371
	s_barrier
	s_branch .LBB0_371
